# HGRN step cross-row sums via permlane swaps instead of LDS shuffles, on top of F
# baseline (speedup 1.0000x reference)
; #define LAS __attribute__((address_space(3)))
; #define HB() asm volatile("s_waitcnt lgkmcnt(0)\n\ts_barrier" ::: "memory")
; template <bool PC> __device__ __forceinline__ void hgrn_unit(LAS unsigned char* lds, int unit, const bf16* P0, const float* lbp, const float* ong, float* Lst, const float* Sst, float* Dtot, bf16* MIX) {
;     ...
;           for (int t = 0; t < 8; ++t) { const float f = __uint_as_float(nf[t] << 16); const float sg = sigmf(f); const float fg = lb + (1.f - lb) * sg; lf[t] = __builtin_amdgcn_logf(fg); ky[t] = 1.f - fg;
;               if (PC) qv[t] = __uint_as_float(nq[t] << 16); }
;         }
;         const v4u cv = nv, ga = ng;
;         if (step < 7) HG_LOAD(step + 1);
; #pragma unroll
;         for (int t = 1; t < 8; ++t) lf[t] += lf[t - 1];
;         { const int s = tid >> 4, c16 = tid & 15; *(LAS v4u*)(lds + HL_V + s * RS + c16 * 16) = cv; }
;         float pre, cl;
;         { const float T = lf[7]; const float p1 = __shfl_up(T, 16), p2 = __shfl_up(T, 32), p3 = __shfl_up(T, 48);
;           pre = (tq >= 1 ? p1 : 0.f) + (tq >= 2 ? p2 : 0.f) + (tq >= 3 ? p3 : 0.f);
;           const float s2 = T + __shfl_xor(T, 16); cl = s2 + __shfl_xor(s2, 32); }
;         const float ecl = __builtin_amdgcn_exp2f(cl);
;         { unsigned kw[4];
; #pragma unroll
;           for (int t = 0; t < 8; t += 2) { const float c0 = pre + lf[t], c1 = pre + lf[t + 1];
;               const float k0 = ky[t] * __builtin_amdgcn_exp2f(-c0), k1 = ky[t + 1] * __builtin_amdgcn_exp2f(-c1);
;               kw[t >> 1] = pk2(k0 * ecl, k1 * ecl);
;               if (PC) { const unsigned kk = pk2(k0, k1), qq = pk2(qv[t] * __builtin_amdgcn_exp2f(c0), qv[t + 1] * __builtin_amdgcn_exp2f(c1));
;                   *(LAS unsigned short*)(lds + HL_KT + (8 * tq + t) * RS + k * 2) = (unsigned short)(kk & 0xffffu);
;                   *(LAS unsigned short*)(lds + HL_KT + (8 * tq + t + 1) * RS + k * 2) = (unsigned short)(kk >> 16);
;                   *(LAS unsigned short*)(lds + HL_QT + (8 * tq + t) * RS + k * 2) = (unsigned short)(qq & 0xffffu);
;                   *(LAS unsigned short*)(lds + HL_QT + (8 * tq + t + 1) * RS + k * 2) = (unsigned short)(qq >> 16); } }
;           *(LAS v4u*)(lds + HL_KE + k * 80 + tq * 16) = (v4u){kw[0], kw[1], kw[2], kw[3]}; }
;         if (tq == 0) DEC[k] = ecl;
;         sumlog += cl;
;         HB();
.LBB0_222:
	v_lshlrev_b32_e32 v86, 16, v86
	v_lshlrev_b32_e32 v87, 16, v87
	v_mul_f32_e32 v86, 0xbfb8aa3b, v86
	v_mul_f32_e32 v87, 0xbfb8aa3b, v87
	v_exp_f32_e32 v86, v86
	v_exp_f32_e32 v87, v87
	v_lshlrev_b32_e32 v80, 16, v80
	v_lshlrev_b32_e32 v84, 16, v84
	v_mul_f32_e32 v80, 0xbfb8aa3b, v80
	v_add_f32_e32 v86, 1.0, v86
	v_add_f32_e32 v87, 1.0, v87
	v_mul_f32_e32 v84, 0xbfb8aa3b, v84
	v_lshlrev_b32_e32 v83, 16, v83
	v_exp_f32_e32 v80, v80
	v_rcp_f32_e32 v86, v86
	v_rcp_f32_e32 v87, v87
	v_lshlrev_b32_e32 v85, 16, v85
	v_exp_f32_e32 v89, v84
	v_mul_f32_e32 v83, 0xbfb8aa3b, v83
	v_mul_f32_e32 v85, 0xbfb8aa3b, v85
	v_exp_f32_e32 v83, v83
	v_exp_f32_e32 v88, v85
	v_add_f32_e32 v80, 1.0, v80
	v_pk_fma_f32 v[84:85], v[50:51], v[86:87], v[48:49]
	v_add_f32_e32 v87, 1.0, v89
	v_rcp_f32_e32 v89, v80
	v_lshlrev_b32_e32 v80, 16, v81
	v_add_f32_e32 v83, 1.0, v83
	v_mul_f32_e32 v80, 0xbfb8aa3b, v80
	v_add_f32_e32 v86, 1.0, v88
	v_rcp_f32_e32 v88, v83
	v_exp_f32_e32 v83, v80
	v_lshlrev_b32_e32 v80, 16, v82
	v_mul_f32_e32 v80, 0xbfb8aa3b, v80
	v_exp_f32_e32 v90, v80
	v_rcp_f32_e32 v86, v86
	v_rcp_f32_e32 v87, v87
	v_add_f32_e32 v82, 1.0, v83
	v_add_f32_e32 v83, 1.0, v90
	v_rcp_f32_e32 v82, v82
	v_rcp_f32_e32 v83, v83
	v_log_f32_e32 v92, v84
	v_log_f32_e32 v93, v85
	v_pk_fma_f32 v[86:87], v[50:51], v[86:87], v[48:49]
	v_pk_fma_f32 v[80:81], v[50:51], v[88:89], v[48:49]
	v_log_f32_e32 v94, v86
	v_log_f32_e32 v95, v87
	v_log_f32_e32 v96, v80
	v_log_f32_e32 v97, v81
	v_pk_add_f32 v[88:89], v[80:81], 1.0 op_sel_hi:[1,0] neg_lo:[1,0] neg_hi:[1,0]
	v_pk_fma_f32 v[80:81], v[50:51], v[82:83], v[48:49]
	ds_write_b128 v42, v[32:35]
	v_log_f32_e32 v82, v80
	v_pk_add_f32 v[90:91], v[80:81], 1.0 op_sel_hi:[1,0] neg_lo:[1,0] neg_hi:[1,0]
	v_add_f32_e32 v80, v92, v93
	v_log_f32_e32 v83, v81
	v_add_f32_e32 v81, v94, v80
	v_add_f32_e32 v93, v95, v81
	v_add_f32_e32 v94, v96, v93
	v_add_f32_e32 v95, v97, v94
	v_add_f32_e32 v96, v82, v95
	v_add_f32_e32 v97, v83, v96
	ds_bpermute_b32 v83, v63, v97
	ds_bpermute_b32 v82, v47, v97
	ds_bpermute_b32 v32, v53, v97
	ds_bpermute_b32 v33, v62, v97
	v_pk_add_f32 v[84:85], v[84:85], 1.0 op_sel_hi:[1,0] neg_lo:[1,0] neg_hi:[1,0]
	s_waitcnt lgkmcnt(3)
	v_add_f32_e32 v35, v97, v83
	s_waitcnt lgkmcnt(2)
	v_cndmask_b32_e64 v34, v82, 0, s[36:37]
	v_mov_b32_e32 v82, v35
	s_waitcnt lgkmcnt(1)
	v_cndmask_b32_e64 v32, 0, v32, s[38:39]
	v_add_f32_e32 v32, v34, v32
	s_waitcnt lgkmcnt(0)
	v_cndmask_b32_e64 v33, 0, v33, s[40:41]
	v_add_f32_e32 v98, v32, v33
	v_permlane32_swap_b32_e32 v82, v35
	s_nop 1
	v_add_f32_e32 v33, v35, v82
	v_add_f32_e32 v34, v92, v98
	v_add_f32_e32 v35, v80, v98
	v_exp_f32_e64 v34, -v34
	v_exp_f32_e64 v35, -v35
	v_exp_f32_e32 v32, v33
	v_add_f32_e32 v80, v81, v98
	v_add_f32_e32 v81, v93, v98
	v_exp_f32_e64 v82, -v80
	v_exp_f32_e64 v83, -v81
	v_pk_mul_f32 v[34:35], v[84:85], v[34:35]
	v_pk_add_f32 v[86:87], v[86:87], 1.0 op_sel_hi:[1,0] neg_lo:[1,0] neg_hi:[1,0]
	v_pk_mul_f32 v[34:35], v[32:33], v[34:35] op_sel_hi:[0,1]
	v_cvt_pk_bf16_f32 v80, v34, v35
	v_pk_mul_f32 v[34:35], v[86:87], v[82:83]
	v_add_f32_e32 v82, v96, v98
	v_pk_mul_f32 v[34:35], v[32:33], v[34:35] op_sel_hi:[0,1]
	v_cvt_pk_bf16_f32 v81, v34, v35
	v_add_f32_e32 v34, v94, v98
	v_add_f32_e32 v35, v95, v98
	v_exp_f32_e64 v34, -v34
	v_exp_f32_e64 v35, -v35
	v_add_f32_e32 v83, v97, v98
	v_exp_f32_e64 v84, -v82
	v_exp_f32_e64 v85, -v83
	v_pk_mul_f32 v[34:35], v[88:89], v[34:35]
	s_nop 0
	v_pk_mul_f32 v[34:35], v[32:33], v[34:35] op_sel_hi:[0,1]
	v_cvt_pk_bf16_f32 v82, v34, v35
	v_pk_mul_f32 v[34:35], v[90:91], v[84:85]
	s_nop 0
	v_pk_mul_f32 v[34:35], v[32:33], v[34:35] op_sel_hi:[0,1]
	v_cvt_pk_bf16_f32 v83, v34, v35
	v_add_u32_e32 v34, v65, v52
	ds_write_b128 v34, v[80:83] offset:26112
	s_and_saveexec_b64 s[18:19], s[36:37]
	ds_write_b32 v69, v32 offset:40960
	s_or_b64 exec, exec, s[18:19]
	s_waitcnt lgkmcnt(0)
	s_barrier
; #define LAS __attribute__((address_space(3)))
; template <bool PC> __device__ __forceinline__ void hgrn_unit(LAS unsigned char* lds, int unit, const bf16* P0, const float* lbp, const float* ong, float* Lst, const float* Sst, float* Dtot, bf16* MIX) {
;     ...
;         const bf16x8 xv = trfrag((const LAS char*)(lds + HL_V + (8 * g + q4) * RS + (16 * wave + 4 * p4) * 2), 4 * RS);
;         bf16x8 xs[4], yq[2][4], ysc[2], yk[8]; float dcv[8];
;         if (PC) {
; #pragma unroll
;             for (int tb = 0; tb < 2; ++tb) ysc[tb] = *(const LAS bf16x8*)(lds + HL_SC + (16 * tb + li) * 80 + g * 16);
; #pragma unroll
;             for (int ks = 0; ks < 4; ++ks) { xs[ks] = trfrag((const LAS char*)(lds + HL_S + (32 * ks + 8 * g + q4) * RS + (16 * wave + 4 * p4) * 2), 4 * RS);
; #pragma unroll
;                 for (int tb = 0; tb < 2; ++tb) yq[tb][ks] = *(const LAS bf16x8*)(lds + HL_QT + (16 * tb + li) * RS + (32 * ks + 8 * g) * 2); }
;         }
; #pragma unroll
;         for (int kb = 0; kb < 8; ++kb) { dcv[kb] = DEC[16 * kb + li]; yk[kb] = *(const LAS bf16x8*)(lds + HL_KE + (16 * kb + li) * 80 + g * 16); }
;         __builtin_amdgcn_sched_barrier(0);
;         if (PC) {
;             f32x4 o[2];
; #pragma unroll
;             for (int tb = 0; tb < 2; ++tb) o[tb] = __builtin_amdgcn_mfma_f32_16x16x32_bf16(xv, ysc[tb], (f32x4){0.f, 0.f, 0.f, 0.f}, 0, 0, 0);
; #pragma unroll
;             for (int ks = 0; ks < 4; ++ks)
; #pragma unroll
;                 for (int tb = 0; tb < 2; ++tb) o[tb] = __builtin_amdgcn_mfma_f32_16x16x32_bf16(xs[ks], yq[tb][ks], o[tb], 0, 0, 0);
; #pragma unroll
;             for (int tb = 0; tb < 2; ++tb) *(LAS f32x4*)(lds + HL_OUT + ((16 * tb + li) * 132 + 16 * wave + 4 * g) * 4) = o[tb];
;         }
; #pragma unroll
;         for (int kb = 0; kb < 8; ++kb) S[kb] = __builtin_amdgcn_mfma_f32_16x16x32_bf16(xv, yk[kb], S[kb] * dcv[kb], 0, 0, 0);
;         HB();
;         if (PC) {
; #pragma unroll
;             for (int kb = 0; kb < 8; ++kb) *(LAS v2u*)(lds + HL_S + (16 * kb + li) * RS + (16 * wave + 4 * g) * 2) = (v2u){pk2(S[kb][0], S[kb][1]), pk2(S[kb][2], S[kb][3])};
;             const int t = tid >> 4, vg = tid & 15;
;             const f32x4 o0 = *(const LAS f32x4*)(lds + HL_OUT + (t * 132 + 8 * vg) * 4), o1 = *(const LAS f32x4*)(lds + HL_OUT + (t * 132 + 8 * vg + 4) * 4);
	v_add_u32_e32 v32, 0xa000, v66
	ds_read_b64_tr_b16 v[80:81], v70
	ds_read_b64_tr_b16 v[82:83], v70 offset:1088
	ds_read2_b32 v[34:35], v32 offset1:16
	ds_read_b128 v[84:87], v71 offset:26112
	ds_read_b128 v[88:91], v71 offset:27392
	ds_read2_b32 v[116:117], v32 offset0:32 offset1:48
	ds_read_b128 v[92:95], v71 offset:28672
	ds_read_b128 v[96:99], v71 offset:29952
	ds_read2_b32 v[118:119], v32 offset0:64 offset1:80
	ds_read_b128 v[100:103], v71 offset:31232
	ds_read_b128 v[104:107], v71 offset:32512
	ds_read2_b32 v[120:121], v32 offset0:96 offset1:112
	ds_read_b128 v[108:111], v71 offset:33792
	ds_read_b128 v[112:115], v71 offset:35072
	s_waitcnt lgkmcnt(11)
	v_mov_b32_e32 v32, v35
	v_pk_mul_f32 v[18:19], v[18:19], v[32:33] op_sel_hi:[1,0]
	v_pk_mul_f32 v[16:17], v[16:17], v[32:33] op_sel_hi:[1,0]
	s_waitcnt lgkmcnt(8)
	v_mov_b32_e32 v32, v117
	v_pk_mul_f32 v[14:15], v[14:15], v[32:33] op_sel_hi:[1,0]
	v_pk_mul_f32 v[12:13], v[12:13], v[32:33] op_sel_hi:[1,0]
	s_waitcnt lgkmcnt(5)
	v_mov_b32_e32 v32, v119
	v_pk_mul_f32 v[10:11], v[10:11], v[32:33] op_sel_hi:[1,0]
	v_pk_mul_f32 v[8:9], v[8:9], v[32:33] op_sel_hi:[1,0]
	s_waitcnt lgkmcnt(2)
	v_mov_b32_e32 v32, v121
	v_pk_mul_f32 v[26:27], v[26:27], v[34:35] op_sel_hi:[1,0]
	v_pk_mul_f32 v[24:25], v[24:25], v[34:35] op_sel_hi:[1,0]
	v_pk_mul_f32 v[22:23], v[22:23], v[116:117] op_sel_hi:[1,0]
	v_pk_mul_f32 v[20:21], v[20:21], v[116:117] op_sel_hi:[1,0]
	v_pk_mul_f32 v[6:7], v[6:7], v[118:119] op_sel_hi:[1,0]
	v_pk_mul_f32 v[4:5], v[4:5], v[118:119] op_sel_hi:[1,0]
	v_pk_mul_f32 v[2:3], v[2:3], v[120:121] op_sel_hi:[1,0]
	v_pk_mul_f32 v[0:1], v[0:1], v[120:121] op_sel_hi:[1,0]
	v_pk_mul_f32 v[30:31], v[30:31], v[32:33] op_sel_hi:[1,0]
	v_pk_mul_f32 v[28:29], v[28:29], v[32:33] op_sel_hi:[1,0]
	v_mfma_f32_16x16x32_bf16 v[24:27], v[80:83], v[84:87], v[24:27]
	s_waitcnt lgkmcnt(0)
	s_barrier
	s_add_i32 s5, s5, 32
	v_add_f32_e32 v45, v45, v33
	v_mfma_f32_16x16x32_bf16 v[16:19], v[80:83], v[88:91], v[16:19]
	s_cmpk_eq_i32 s5, 0x100
	v_mfma_f32_16x16x32_bf16 v[20:23], v[80:83], v[92:95], v[20:23]
	v_mfma_f32_16x16x32_bf16 v[12:15], v[80:83], v[96:99], v[12:15]
	v_mfma_f32_16x16x32_bf16 v[4:7], v[80:83], v[100:103], v[4:7]
	v_mfma_f32_16x16x32_bf16 v[8:11], v[80:83], v[104:107], v[8:11]
	s_waitcnt lgkmcnt(1)
	v_mfma_f32_16x16x32_bf16 v[0:3], v[80:83], v[108:111], v[0:3]
	s_waitcnt lgkmcnt(0)
	v_mfma_f32_16x16x32_bf16 v[28:31], v[80:83], v[112:115], v[28:31]
	s_cbranch_scc0 .LBB0_220
	s_ashr_i32 s43, s42, 31
	s_lshl_b64 s[14:15], s[42:43], 16
	s_add_u32 s14, s44, s14
	s_addc_u32 s15, s45, s15
	v_ashrrev_i32_e32 v47, 31, v46
	v_lshl_add_u64 v[32:33], v[46:47], 2, s[14:15]
	v_mov_b32_e32 v53, v43
	v_lshl_add_u64 v[32:33], v[32:33], 0, v[52:53]
	v_lshlrev_b32_e32 v42, 9, v61
	v_lshl_add_u64 v[32:33], v[32:33], 0, v[42:43]
	s_movk_i32 s5, 0x2000
	global_store_dwordx4 v[32:33], v[24:27], off sc1
	s_nop 1
	v_add_co_u32_e32 v24, vcc, s5, v32
	s_nop 1
	v_addc_co_u32_e32 v25, vcc, 0, v33, vcc
	global_store_dwordx4 v[24:25], v[16:19], off sc1
	s_nop 1
	v_add_co_u32_e32 v16, vcc, s75, v32
	s_nop 1
	v_addc_co_u32_e32 v17, vcc, 0, v33, vcc
	global_store_dwordx4 v[16:17], v[20:23], off sc1
	v_add_co_u32_e32 v16, vcc, s76, v32
	s_nop 1
	v_addc_co_u32_e32 v17, vcc, 0, v33, vcc
	global_store_dwordx4 v[16:17], v[12:15], off sc1
	s_nop 1
	v_add_co_u32_e32 v12, vcc, 0x8000, v32
	s_nop 1
	v_addc_co_u32_e32 v13, vcc, 0, v33, vcc
	global_store_dwordx4 v[12:13], v[4:7], off sc1
	s_nop 1
	v_add_co_u32_e32 v4, vcc, 0xa000, v32
	s_nop 1
	v_addc_co_u32_e32 v5, vcc, 0, v33, vcc
	global_store_dwordx4 v[4:5], v[8:11], off sc1
	v_add_co_u32_e32 v4, vcc, 0xc000, v32
	s_nop 1
	v_addc_co_u32_e32 v5, vcc, 0, v33, vcc
	global_store_dwordx4 v[4:5], v[0:3], off sc1
	s_nop 1
	v_add_co_u32_e32 v0, vcc, 0xe000, v32
	s_nop 1
	v_addc_co_u32_e32 v1, vcc, 0, v33, vcc
	global_store_dwordx4 v[0:1], v[28:31], off sc1
	s_and_saveexec_b64 s[18:19], s[36:37]
	s_cbranch_execz .LBB0_218
	v_exp_f32_e32 v2, v45
	v_lshl_add_u32 v0, s42, 7, v44
	v_ashrrev_i32_e32 v1, 31, v0
	v_lshl_add_u64 v[0:1], v[0:1], 2, s[0:1]
	global_store_dword v[0:1], v2, off sc1
	s_branch .LBB0_218

; template <bool PC> __device__ __forceinline__ void hgrn_unit(LAS unsigned char* lds, int unit, const bf16* P0, const float* lbp, const float* ong, float* Lst, const float* Sst, float* Dtot, bf16* MIX) {
;     ...
;           for (int t = 0; t < 8; ++t) { const float f = __uint_as_float(nf[t] << 16); const float sg = sigmf(f); const float fg = lb + (1.f - lb) * sg; lf[t] = __builtin_amdgcn_logf(fg); ky[t] = 1.f - fg;
;               if (PC) qv[t] = __uint_as_float(nq[t] << 16); }
;         }
;         const v4u cv = nv, ga = ng;
;         if (step < 7) HG_LOAD(step + 1);
; #pragma unroll
;         for (int t = 1; t < 8; ++t) lf[t] += lf[t - 1];
;         { const int s = tid >> 4, c16 = tid & 15; *(LAS v4u*)(lds + HL_V + s * RS + c16 * 16) = cv; }
;         float pre, cl;
;         { const float T = lf[7]; const float p1 = __shfl_up(T, 16), p2 = __shfl_up(T, 32), p3 = __shfl_up(T, 48);
;           pre = (tq >= 1 ? p1 : 0.f) + (tq >= 2 ? p2 : 0.f) + (tq >= 3 ? p3 : 0.f);
;           const float s2 = T + __shfl_xor(T, 16); cl = s2 + __shfl_xor(s2, 32); }
;         const float ecl = __builtin_amdgcn_exp2f(cl);
;         { unsigned kw[4];
; #pragma unroll
;           for (int t = 0; t < 8; t += 2) { const float c0 = pre + lf[t], c1 = pre + lf[t + 1];
;               const float k0 = ky[t] * __builtin_amdgcn_exp2f(-c0), k1 = ky[t + 1] * __builtin_amdgcn_exp2f(-c1);
;               kw[t >> 1] = pk2(k0 * ecl, k1 * ecl);
;               if (PC) { const unsigned kk = pk2(k0, k1), qq = pk2(qv[t] * __builtin_amdgcn_exp2f(c0), qv[t + 1] * __builtin_amdgcn_exp2f(c1));
;                   *(LAS unsigned short*)(lds + HL_KT + (8 * tq + t) * RS + k * 2) = (unsigned short)(kk & 0xffffu);
;                   *(LAS unsigned short*)(lds + HL_KT + (8 * tq + t + 1) * RS + k * 2) = (unsigned short)(kk >> 16);
;                   *(LAS unsigned short*)(lds + HL_QT + (8 * tq + t) * RS + k * 2) = (unsigned short)(qq & 0xffffu);
;                   *(LAS unsigned short*)(lds + HL_QT + (8 * tq + t + 1) * RS + k * 2) = (unsigned short)(qq >> 16); } }
;           *(LAS v4u*)(lds + HL_KE + k * 80 + tq * 16) = (v4u){kw[0], kw[1], kw[2], kw[3]}; }
;         if (tq == 0) DEC[k] = ecl;
;         sumlog += cl;
;         HB();
;         if (PC) {
;             if (wave < 4) {
;                 const int ti = wave >> 1, si = wave & 1;
;                 f32x4 a = (f32x4){0.f, 0.f, 0.f, 0.f};
.LBB0_464:
	v_lshlrev_b32_e32 v93, 16, v93
	v_lshlrev_b32_e32 v92, 16, v92
	v_mul_f32_e32 v93, 0xbfb8aa3b, v93
	v_mul_f32_e32 v92, 0xbfb8aa3b, v92
	v_exp_f32_e32 v93, v93
	v_exp_f32_e32 v92, v92
	v_lshlrev_b32_e32 v89, 16, v89
	v_lshlrev_b32_e32 v88, 16, v88
	v_mul_f32_e32 v89, 0xbfb8aa3b, v89
	v_mul_f32_e32 v88, 0xbfb8aa3b, v88
	v_add_f32_e32 v93, 1.0, v93
	v_add_f32_e32 v92, 1.0, v92
	v_exp_f32_e32 v89, v89
	v_exp_f32_e32 v88, v88
	v_rcp_f32_e32 v148, v93
	v_rcp_f32_e32 v149, v92
	v_lshlrev_b32_e32 v91, 16, v91
	v_lshlrev_b32_e32 v90, 16, v90
	v_mul_f32_e32 v91, 0xbfb8aa3b, v91
	v_mul_f32_e32 v90, 0xbfb8aa3b, v90
	v_add_f32_e32 v89, 1.0, v89
	v_add_f32_e32 v88, 1.0, v88
	v_exp_f32_e32 v91, v91
	v_exp_f32_e32 v90, v90
	v_pk_fma_f32 v[92:93], v[62:63], v[148:149], v[60:61]
	v_rcp_f32_e32 v148, v89
	v_rcp_f32_e32 v149, v88
	v_lshlrev_b32_e32 v95, 16, v95
	v_lshlrev_b32_e32 v94, 16, v94
	v_mul_f32_e32 v95, 0xbfb8aa3b, v95
	v_mul_f32_e32 v94, 0xbfb8aa3b, v94
	v_add_f32_e32 v91, 1.0, v91
	v_add_f32_e32 v90, 1.0, v90
	v_exp_f32_e32 v95, v95
	v_exp_f32_e32 v94, v94
	v_pk_fma_f32 v[88:89], v[62:63], v[148:149], v[60:61]
	v_rcp_f32_e32 v148, v91
	v_rcp_f32_e32 v149, v90
	v_add_f32_e32 v95, 1.0, v95
	v_add_f32_e32 v94, 1.0, v94
	v_log_f32_e32 v147, v92
	v_log_f32_e32 v150, v93
	v_pk_fma_f32 v[90:91], v[62:63], v[148:149], v[60:61]
	v_rcp_f32_e32 v148, v95
	v_rcp_f32_e32 v149, v94
	v_log_f32_e32 v151, v88
	v_log_f32_e32 v152, v89
	v_log_f32_e32 v153, v90
	v_log_f32_e32 v154, v91
	v_pk_fma_f32 v[94:95], v[62:63], v[148:149], v[60:61]
	v_add_f32_e32 v150, v147, v150
	v_log_f32_e32 v148, v94
	v_add_f32_e32 v151, v151, v150
	v_log_f32_e32 v149, v95
	v_add_f32_e32 v152, v152, v151
	v_add_f32_e32 v153, v153, v152
	v_add_f32_e32 v154, v154, v153
	v_add_f32_e32 v155, v148, v154
	v_add_f32_e32 v156, v149, v155
	ds_write_b128 v122, v[52:55]
	ds_bpermute_b32 v52, v107, v156
	ds_bpermute_b32 v53, v108, v156
	ds_bpermute_b32 v54, v109, v156
	v_pk_add_f32 v[92:93], v[92:93], 1.0 op_sel_hi:[1,0] neg_lo:[1,0] neg_hi:[1,0]
	v_lshlrev_b32_e32 v87, 16, v87
	s_waitcnt lgkmcnt(2)
	v_cndmask_b32_e64 v52, v52, 0, s[38:39]
	s_waitcnt lgkmcnt(1)
	v_cndmask_b32_e64 v53, 0, v53, s[40:41]
	v_add_f32_e32 v52, v52, v53
	s_waitcnt lgkmcnt(0)
	v_cndmask_b32_e64 v53, 0, v54, s[42:43]
	v_add_f32_e32 v53, v52, v53
	v_mov_b32_e32 v52, v156
	v_mov_b32_e32 v54, v156
	v_add_f32_e32 v147, v147, v53
	v_add_f32_e32 v149, v150, v53
	v_exp_f32_e64 v55, -v149
	v_lshlrev_b32_e32 v86, 16, v86
	s_waitcnt lgkmcnt(0)
	v_permlane16_swap_b32_e32 v52, v54
	s_nop 1
	v_add_f32_e32 v52, v52, v54
	v_mov_b32_e32 v54, v52
	v_pk_add_f32 v[88:89], v[88:89], 1.0 op_sel_hi:[1,0] neg_lo:[1,0] neg_hi:[1,0]
	v_lshlrev_b32_e32 v85, 16, v85
	v_lshlrev_b32_e32 v84, 16, v84
	v_pk_add_f32 v[90:91], v[90:91], 1.0 op_sel_hi:[1,0] neg_lo:[1,0] neg_hi:[1,0]
	s_waitcnt lgkmcnt(0)
	v_permlane32_swap_b32_e32 v54, v52
	s_nop 1
	v_add_f32_e32 v52, v52, v54
	v_exp_f32_e64 v54, -v147
	v_exp_f32_e32 v52, v52
	v_lshlrev_b32_e32 v83, 16, v83
	v_lshlrev_b32_e32 v82, 16, v82
	v_pk_mul_f32 v[54:55], v[92:93], v[54:55]
	v_pk_add_f32 v[94:95], v[94:95], 1.0 op_sel_hi:[1,0] neg_lo:[1,0] neg_hi:[1,0]
	v_pk_mul_f32 v[92:93], v[52:53], v[54:55] op_sel_hi:[0,1]
	v_cvt_pk_bf16_f32 v148, v92, v93
	v_cvt_pk_bf16_f32 v92, v54, v55
	v_exp_f32_e32 v54, v147
	v_exp_f32_e32 v55, v149
	v_add_f32_e32 v93, v152, v53
	v_lshlrev_b32_e32 v81, 16, v81
	v_lshlrev_b32_e32 v80, 16, v80
	v_pk_mul_f32 v[54:55], v[54:55], v[86:87]
	s_nop 0
	v_cvt_pk_bf16_f32 v54, v54, v55
	ds_write_b16 v123, v92 offset:17408
	ds_write_b16_d16_hi v123, v92 offset:17680
	ds_write_b16 v123, v54 offset:8704
	ds_write_b16_d16_hi v123, v54 offset:8976
	v_add_f32_e32 v92, v151, v53
	v_exp_f32_e64 v54, -v92
	v_exp_f32_e64 v55, -v93
	s_nop 0
	v_pk_mul_f32 v[54:55], v[88:89], v[54:55]
	s_nop 0
	v_pk_mul_f32 v[86:87], v[52:53], v[54:55] op_sel_hi:[0,1]
	v_cvt_pk_bf16_f32 v149, v86, v87
	v_cvt_pk_bf16_f32 v86, v54, v55
	v_exp_f32_e32 v54, v92
	v_exp_f32_e32 v55, v93
	v_add_f32_e32 v87, v154, v53
	v_pk_mul_f32 v[54:55], v[54:55], v[84:85]
	s_nop 0
	v_cvt_pk_bf16_f32 v54, v54, v55
	ds_write_b16 v123, v86 offset:17952
	ds_write_b16_d16_hi v123, v86 offset:18224
	ds_write_b16 v123, v54 offset:9248
	ds_write_b16_d16_hi v123, v54 offset:9520
	v_add_f32_e32 v86, v153, v53
	v_exp_f32_e64 v54, -v86
	v_exp_f32_e64 v55, -v87
	s_nop 0
	v_pk_mul_f32 v[54:55], v[90:91], v[54:55]
	s_nop 0
	v_pk_mul_f32 v[84:85], v[52:53], v[54:55] op_sel_hi:[0,1]
	v_cvt_pk_bf16_f32 v150, v84, v85
	v_cvt_pk_bf16_f32 v84, v54, v55
	v_exp_f32_e32 v54, v86
	v_exp_f32_e32 v55, v87
	s_nop 0
	v_pk_mul_f32 v[54:55], v[54:55], v[82:83]
	s_nop 0
	v_cvt_pk_bf16_f32 v54, v54, v55
	ds_write_b16 v123, v84 offset:18496
	ds_write_b16_d16_hi v123, v84 offset:18768
	ds_write_b16 v123, v54 offset:9792
	ds_write_b16_d16_hi v123, v54 offset:10064
	v_add_f32_e32 v84, v155, v53
	v_add_f32_e32 v53, v156, v53
	v_exp_f32_e64 v54, -v84
	v_exp_f32_e64 v55, -v53
	s_nop 0
	v_pk_mul_f32 v[54:55], v[94:95], v[54:55]
	s_nop 0
	v_pk_mul_f32 v[82:83], v[52:53], v[54:55] op_sel_hi:[0,1]
	v_cvt_pk_bf16_f32 v151, v82, v83
	v_cvt_pk_bf16_f32 v82, v54, v55
	v_exp_f32_e32 v54, v84
	v_exp_f32_e32 v55, v53
	s_nop 0
	v_pk_mul_f32 v[54:55], v[54:55], v[80:81]
	s_nop 0
	v_cvt_pk_bf16_f32 v53, v54, v55
	ds_write_b16 v123, v82 offset:19040
	ds_write_b16_d16_hi v123, v82 offset:19312
	ds_write_b16 v123, v53 offset:10336
	ds_write_b16_d16_hi v123, v53 offset:10608
	v_add_u32_e32 v53, v64, v56
	ds_write_b128 v53, v[148:151] offset:26112
	s_and_saveexec_b64 s[18:19], s[38:39]
	ds_write_b32 v124, v52 offset:40960
	s_or_b64 exec, exec, s[18:19]
	s_waitcnt lgkmcnt(0)
	s_barrier
	s_and_saveexec_b64 s[18:19], s[44:45]
	s_cbranch_execz .LBB0_461
	v_mov_b32_e32 v52, 0
	v_mov_b32_e32 v53, 0
	v_mov_b32_e32 v54, 0
	v_mov_b32_e32 v55, 0
	s_and_saveexec_b64 s[66:67], s[46:47]
	s_cbranch_execz .LBB0_460
	ds_read_b128 v[52:55], v125 offset:17408
	v_add_u32_e32 v147, v65, v56
	ds_read_b128 v[80:83], v125 offset:17472
	ds_read_b128 v[84:87], v147 offset:8704
	ds_read_b128 v[88:91], v147 offset:8768
	s_waitcnt lgkmcnt(1)
	v_mfma_f32_16x16x32_bf16 v[52:55], v[52:55], v[84:87], 0
	ds_read_b128 v[84:87], v125 offset:17536
	ds_read_b128 v[92:95], v125 offset:17600
	s_waitcnt lgkmcnt(2)
	v_mfma_f32_16x16x32_bf16 v[52:55], v[80:83], v[88:91], v[52:55]
	ds_read_b128 v[80:83], v147 offset:8832
	ds_read_b128 v[88:91], v147 offset:8896
	s_waitcnt lgkmcnt(1)
	v_mfma_f32_16x16x32_bf16 v[52:55], v[84:87], v[80:83], v[52:55]
	s_waitcnt lgkmcnt(0)
	v_mfma_f32_16x16x32_bf16 v[52:55], v[92:95], v[88:91], v[52:55]
	s_and_saveexec_b64 s[76:77], s[48:49]
	s_cbranch_execz .LBB0_459
	v_mov_b32_e32 v80, s1
	s_nop 4
	v_cndmask_b32_e64 v80, v52, v80, s[50:51]
	v_cndmask_b32_e64 v53, 0, v53, s[52:53]
	v_cndmask_b32_e64 v52, v80, v52, s[52:53]
	v_cndmask_b32_e64 v54, v54, 0, s[54:55]
	v_cndmask_b32_e64 v55, v55, 0, s[56:57]
	s_branch .LBB0_459
